# C/B loops: packed f32 adds replaced by scalar adds, exp block in-place with serial sum
# baseline (speedup 1.0000x reference)
; template <int MODE> __device__ __forceinline__ void attn_unit(FLAS unsigned char* lds, const Unit u) {
;     ...
;     for (int t = u.t_lo; t < u.t_hi; ++t) {
;         const int cur = (t - u.t_lo) & 1;
;         const bool more = (t + 1 < u.t_hi);
;         if (more) { kreg = *(const u32x4*)(ksrc + (size_t)(t + 1) * 64 * u.ldk);
; #pragma unroll
;             for (int i = 0; i < NVR; ++i) vreg[i] = *(const u32x4*)(vsrc + (size_t)i * 64 * MTOK + (t + 1) * 64); }
;         const int k0 = t * 64;
;         bool active = true;
;         if (MODE == 1) active = (t >= rstart) && (t < rstart + 8);
;         if (MODE == 2) active = (k0 + 63 >= q0w - 1024) && (k0 <= q0w + 31 + 1024);
;         if (active) {
;             f32x16 p0, p1;
;             bf16x8 kf[8];
;             { const FLAS unsigned char* kb = lds + L_K + cur * KBUF;
; #pragma unroll
;               for (int d0 = 0; d0 < 4; ++d0) { const int ko = (2 * d0 + hi) * 1024 + ((r32 ^ (2 * d0 + hi)) * 16); kf[2 * d0] = *(const FLAS bf16x8*)(kb + ko); kf[2 * d0 + 1] = *(const FLAS bf16x8*)(kb + ko + 512); } }
;             float cb = 0.f; bool zinit = false;
;             if (MODE == 0) { const int dmin = k0 - (q0w + 31), dmax = k0 + 63 - q0w;
;                 if (dmin >= 559) { cb = L[LUT_C + 600]; zinit = true; } else if (dmax <= -559) { cb = L[LUT_C - 600]; zinit = true; } }
;             if (zinit) {
;                 const f32x16 z16 = {0.f,0.f,0.f,0.f,0.f,0.f,0.f,0.f,0.f,0.f,0.f,0.f,0.f,0.f,0.f,0.f};
;                 FA_SB();
;                 p0 = __builtin_amdgcn_mfma_f32_32x32x16_bf16(kf[0], qr[0], z16, 0, 0, 0); p1 = __builtin_amdgcn_mfma_f32_32x32x16_bf16(kf[1], qr[0], z16, 0, 0, 0);
; #pragma unroll
;                 for (int d0 = 1; d0 < 4; ++d0) { p0 = __builtin_amdgcn_mfma_f32_32x32x16_bf16(kf[2 * d0], qr[d0], p0, 0, 0, 0); p1 = __builtin_amdgcn_mfma_f32_32x32x16_bf16(kf[2 * d0 + 1], qr[d0], p1, 0, 0, 0); }
;             } else {
;                 if (MODE == 0 || MODE == 2) { const FLAS float* lp = L + (k0 - q + LUT_C + 4 * hi);
; #pragma unroll
;                     for (int r = 0; r < 16; ++r) { p0[r] = lp[(r & 3) + 8 * (r >> 2)]; p1[r] = lp[32 + (r & 3) + 8 * (r >> 2)]; }
;                 } else { const FLAS float* lp = L + ((t - gi + 7) * 128 + 63 - qc + 4 * hi);
; #pragma unroll
;                     for (int r = 0; r < 16; ++r) { const int kc = (r & 3) + 8 * (r >> 2) + 4 * hi;
.LBB0_498:
	s_and_b32 s24, s8, 1
	s_add_i32 s9, s22, 63
	s_cmp_ge_i32 s9, s12
	s_cselect_b64 s[34:35], -1, 0
	s_cmp_le_i32 s22, s21
	s_cselect_b64 s[38:39], -1, 0
	s_and_b64 s[34:35], s[34:35], s[38:39]
	s_andn2_b64 vcc, exec, s[34:35]
	s_cbranch_vccnz .LBB0_506
	s_lshl_b32 s9, s24, 13
	s_add_i32 s9, s9, 0
	v_add3_u32 v32, s9, v139, v140
	ds_read_b128 v[88:91], v32
	ds_read_b128 v[92:95], v32 offset:512
	v_add3_u32 v32, s9, v141, v142
	ds_read_b128 v[102:105], v32
	ds_read_b128 v[106:109], v32 offset:512
	v_add3_u32 v32, s9, v143, v144
	ds_read_b128 v[110:113], v32
	ds_read_b128 v[114:117], v32 offset:512
	v_add3_u32 v32, s9, v145, v146
	ds_read_b128 v[118:121], v32
	ds_read_b128 v[122:125], v32 offset:512
	ds_read2_b32 v[32:33], v147 offset1:1
	ds_read2_b32 v[34:35], v147 offset0:2 offset1:3
	ds_read2_b32 v[36:37], v147 offset0:8 offset1:9
	ds_read2_b32 v[38:39], v147 offset0:10 offset1:11
	ds_read2_b32 v[48:49], v147 offset0:32 offset1:33
	ds_read2_b32 v[50:51], v147 offset0:34 offset1:35
	ds_read2_b32 v[52:53], v147 offset0:40 offset1:41
	ds_read2_b32 v[54:55], v147 offset0:42 offset1:43
	ds_read2_b32 v[40:41], v147 offset0:16 offset1:17
	ds_read2_b32 v[42:43], v147 offset0:18 offset1:19
	ds_read2_b32 v[44:45], v147 offset0:24 offset1:25
	ds_read2_b32 v[46:47], v147 offset0:26 offset1:27
	ds_read2_b32 v[56:57], v147 offset0:48 offset1:49
	ds_read2_b32 v[58:59], v147 offset0:50 offset1:51
	ds_read2_b32 v[60:61], v147 offset0:56 offset1:57
	ds_read2_b32 v[62:63], v147 offset0:58 offset1:59
	s_xor_b64 s[6:7], s[6:7], -1
	s_waitcnt lgkmcnt(4)
	v_mfma_f32_32x32x16_bf16 v[32:47], v[88:91], v[64:67], v[32:47]
	s_mul_i32 s9, s24, 0x4800
	v_add_u32_e32 v149, s9, v138
	s_waitcnt lgkmcnt(0)
	v_mfma_f32_32x32x16_bf16 v[48:63], v[92:95], v[64:67], v[48:63]
	ds_read_b128 v[92:95], v149 offset:16384
	ds_read_b128 v[88:91], v149 offset:20992
	v_mfma_f32_32x32x16_bf16 v[32:47], v[102:105], v[68:71], v[32:47]
	v_mfma_f32_32x32x16_bf16 v[48:63], v[106:109], v[68:71], v[48:63]
	v_mfma_f32_32x32x16_bf16 v[32:47], v[110:113], v[72:75], v[32:47]
	v_mfma_f32_32x32x16_bf16 v[48:63], v[114:117], v[72:75], v[48:63]
	v_mfma_f32_32x32x16_bf16 v[32:47], v[118:121], v[76:79], v[32:47]
	v_mfma_f32_32x32x16_bf16 v[48:63], v[122:125], v[76:79], v[48:63]
	s_and_b32 s8, s8, 3
	s_cmp_lg_u32 s8, 0
	s_cselect_b64 s[8:9], -1, 0
	v_sub_f32_e32 v102, 0, v148
	s_and_b64 s[8:9], s[6:7], s[8:9]
	s_nop 5
	v_add_f32_e32 v132, v102, v32
	v_add_f32_e32 v133, v102, v33
	v_add_f32_e32 v120, v102, v48
	v_add_f32_e32 v121, v102, v49
	v_add_f32_e32 v130, v102, v34
	v_add_f32_e32 v131, v102, v35
	v_add_f32_e32 v116, v102, v50
	v_add_f32_e32 v117, v102, v51
	v_add_f32_e32 v128, v102, v36
	v_add_f32_e32 v129, v102, v37
	v_add_f32_e32 v114, v102, v52
	v_add_f32_e32 v115, v102, v53
	v_add_f32_e32 v126, v102, v38
	v_add_f32_e32 v127, v102, v39
	v_add_f32_e32 v110, v102, v54
	v_add_f32_e32 v111, v102, v55
	v_add_f32_e32 v124, v102, v40
	v_add_f32_e32 v125, v102, v41
	v_add_f32_e32 v108, v102, v56
	v_add_f32_e32 v109, v102, v57
	v_add_f32_e32 v122, v102, v42
	v_add_f32_e32 v123, v102, v43
	v_add_f32_e32 v106, v102, v58
	v_add_f32_e32 v107, v102, v59
	v_add_f32_e32 v118, v102, v44
	v_add_f32_e32 v119, v102, v45
	v_add_f32_e32 v104, v102, v60
	v_add_f32_e32 v105, v102, v61
	v_add_f32_e32 v112, v102, v46
	v_add_f32_e32 v113, v102, v47
	v_add_f32_e32 v103, v102, v63
	v_add_f32_e32 v102, v102, v62
	s_and_b64 vcc, exec, s[8:9]
	s_mov_b32 s25, 0x41000000
	s_cbranch_vccnz .LBB0_507
; __device__ __forceinline__ float xhalf_max(float m) { unsigned a = __builtin_bit_cast(unsigned, m), b = a; xswap(a, b); return __builtin_fmaxf(__builtin_bit_cast(float, a), __builtin_bit_cast(float, b)); }
; template <int MODE> __device__ __forceinline__ void attn_unit(FLAS unsigned char* lds, const Unit u) {
;     ...
;             if (first || (((t - u.t_lo) & 3) == 0)) {
;             float rm = __builtin_fmaxf(p0[0], p1[0]);
; #pragma unroll
;             for (int r = 1; r < 16; ++r) rm = __builtin_fmaxf(rm, __builtin_fmaxf(p0[r], p1[r]));
;             rm = xhalf_max(rm);
;             if (first) {
;                 const float dl = __builtin_fmaxf(rm, -1000.0f); mrun = dl;
; #pragma unroll
;                 for (int r = 0; r < 16; ++r) { p0[r] = p0[r] - dl; p1[r] = p1[r] - dl; }
;                 first = false;
;             } else if (__any(rm > 8.0f)) { const float dl = __builtin_fmaxf(rm, 0.0f); const float f = __builtin_amdgcn_exp2f(-dl); mrun += dl; lsum *= f;
; #pragma unroll
;                 for (int i = 0; i < NDB; ++i) o[i] = o[i] * f;
; #pragma unroll
;                 for (int r = 0; r < 16; ++r) { p0[r] = p0[r] - dl; p1[r] = p1[r] - dl; } }
	v_max_f32_e32 v32, v121, v121
	v_max_f32_e32 v33, v133, v133
	v_max_f32_e32 v32, v33, v32
	v_max_f32_e32 v33, v116, v116
	v_max_f32_e32 v34, v130, v130
	v_max_f32_e32 v33, v34, v33
	v_max_f32_e32 v34, v117, v117
	v_max_f32_e32 v35, v131, v131
	v_max3_f32 v32, v132, v120, v32
	v_max_f32_e32 v34, v35, v34
	v_max3_f32 v32, v32, v33, v34
	v_max_f32_e32 v33, v114, v114
	v_max_f32_e32 v34, v128, v128
	v_max_f32_e32 v33, v34, v33
	v_max_f32_e32 v34, v115, v115
	v_max_f32_e32 v35, v129, v129
	v_max_f32_e32 v34, v35, v34
	v_max3_f32 v32, v32, v33, v34
	v_max_f32_e32 v33, v110, v110
	v_max_f32_e32 v34, v126, v126
	v_max_f32_e32 v33, v34, v33
	v_max_f32_e32 v34, v111, v111
	v_max_f32_e32 v35, v127, v127
	v_max_f32_e32 v34, v35, v34
	v_max3_f32 v32, v32, v33, v34
	v_max_f32_e32 v33, v108, v108
	v_max_f32_e32 v34, v124, v124
	v_max_f32_e32 v33, v34, v33
	v_max_f32_e32 v34, v109, v109
	v_max_f32_e32 v35, v125, v125
	v_max_f32_e32 v34, v35, v34
	v_max3_f32 v32, v32, v33, v34
	v_max_f32_e32 v33, v106, v106
	v_max_f32_e32 v34, v122, v122
	v_max_f32_e32 v33, v34, v33
	v_max_f32_e32 v34, v107, v107
	v_max_f32_e32 v35, v123, v123
	v_max_f32_e32 v34, v35, v34
	v_max3_f32 v32, v32, v33, v34
	v_max_f32_e32 v33, v104, v104
	v_max_f32_e32 v34, v118, v118
	v_max_f32_e32 v33, v34, v33
	v_max_f32_e32 v34, v105, v105
	v_max_f32_e32 v35, v119, v119
	v_max_f32_e32 v34, v35, v34
	v_max3_f32 v32, v32, v33, v34
	v_max_f32_e32 v33, v102, v102
	v_max_f32_e32 v34, v112, v112
	v_max_f32_e32 v33, v34, v33
	v_max_f32_e32 v34, v103, v103
	v_max_f32_e32 v35, v113, v113
	v_max_f32_e32 v34, v35, v34
	v_max3_f32 v32, v32, v33, v34
	v_mov_b32_e32 v33, v32
	s_nop 1
	v_permlane32_swap_b32 v32, v33
	s_nop 1
	s_mov_b64 s[8:9], -1
	v_max_f32_e32 v33, v33, v33
	v_max_f32_e32 v32, v32, v32
	v_max_f32_e32 v164, v32, v33
	s_and_b64 vcc, exec, s[6:7]
	s_movk_i32 s38, 0x87f
	s_mov_b64 s[34:35], 0x800
	s_cbranch_vccz .LBB0_503
	v_cmp_lt_f32_e32 vcc, s25, v164
	s_cbranch_vccz .LBB0_508
	v_max_f32_e32 v32, v164, v164
	v_max_f32_e32 v167, 0, v32
	v_exp_f32_e64 v184, -v167
	v_add_f32_e32 v148, v148, v167
	v_sub_f32_e32 v166, v132, v167
	v_sub_f32_e32 v165, v133, v167
	v_pk_mul_f32 v[62:63], v[30:31], v[184:185] op_sel_hi:[1,0]
	v_pk_mul_f32 v[60:61], v[28:29], v[184:185] op_sel_hi:[1,0]
	v_pk_mul_f32 v[58:59], v[26:27], v[184:185] op_sel_hi:[1,0]
	v_pk_mul_f32 v[56:57], v[24:25], v[184:185] op_sel_hi:[1,0]
	v_pk_mul_f32 v[54:55], v[22:23], v[184:185] op_sel_hi:[1,0]
	v_pk_mul_f32 v[52:53], v[20:21], v[184:185] op_sel_hi:[1,0]
	v_pk_mul_f32 v[50:51], v[18:19], v[184:185] op_sel_hi:[1,0]
	v_pk_mul_f32 v[48:49], v[16:17], v[184:185] op_sel_hi:[1,0]
	v_pk_mul_f32 v[46:47], v[14:15], v[184:185] op_sel_hi:[1,0]
	v_pk_mul_f32 v[44:45], v[12:13], v[184:185] op_sel_hi:[1,0]
	v_pk_mul_f32 v[42:43], v[10:11], v[184:185] op_sel_hi:[1,0]
	v_pk_mul_f32 v[40:41], v[8:9], v[184:185] op_sel_hi:[1,0]
	v_pk_mul_f32 v[38:39], v[6:7], v[184:185] op_sel_hi:[1,0]
	v_pk_mul_f32 v[36:37], v[4:5], v[184:185] op_sel_hi:[1,0]
	v_pk_mul_f32 v[34:35], v[2:3], v[184:185] op_sel_hi:[1,0]
	v_pk_mul_f32 v[32:33], v[0:1], v[184:185] op_sel_hi:[1,0]
	v_sub_f32_e32 v163, v130, v167
	v_sub_f32_e32 v162, v131, v167
	v_sub_f32_e32 v161, v128, v167
	v_sub_f32_e32 v160, v129, v167
	v_sub_f32_e32 v159, v126, v167
	v_sub_f32_e32 v158, v127, v167
	v_sub_f32_e32 v157, v124, v167
	v_sub_f32_e32 v156, v125, v167
	v_sub_f32_e32 v155, v122, v167
	v_sub_f32_e32 v154, v123, v167
	v_sub_f32_e32 v153, v118, v167
	v_sub_f32_e32 v152, v119, v167
	v_sub_f32_e32 v151, v112, v167
	v_sub_f32_e32 v150, v113, v167
	v_sub_f32_e32 v182, v120, v167
	v_sub_f32_e32 v181, v121, v167
	v_sub_f32_e32 v180, v116, v167
	v_sub_f32_e32 v179, v117, v167
	v_sub_f32_e32 v178, v114, v167
	v_sub_f32_e32 v177, v115, v167
	v_sub_f32_e32 v176, v110, v167
	v_sub_f32_e32 v175, v111, v167
	v_sub_f32_e32 v174, v108, v167
	v_sub_f32_e32 v173, v109, v167
	v_sub_f32_e32 v172, v106, v167
	v_sub_f32_e32 v171, v107, v167
	v_sub_f32_e32 v170, v104, v167
	v_sub_f32_e32 v169, v105, v167
	v_sub_f32_e32 v168, v102, v167
	v_sub_f32_e32 v167, v103, v167
	v_mul_f32_e32 v183, v137, v184
	s_mov_b64 s[8:9], 0

; #define FLAS __attribute__((address_space(3)))
; #define FA_SB() __builtin_amdgcn_sched_barrier(0)
; __device__ __forceinline__ unsigned cvtpk(float lo, float hi) { f32x2_t v = {lo, hi}; bf16x2_t b = __builtin_convertvector(v, bf16x2_t); return __builtin_bit_cast(unsigned, b); }
; template <int MODE> __device__ __forceinline__ void attn_unit(FLAS unsigned char* lds, const Unit u) {
;     ...
;             float ps = 0.f;
; #pragma unroll
;             for (int r = 0; r < 16; ++r) { p0[r] = __builtin_amdgcn_exp2f(p0[r]); p1[r] = __builtin_amdgcn_exp2f(p1[r]); ps += p0[r] + p1[r]; }
;             lsum += ps;
;             u32x4 pw[4];
;             pw[0] = (u32x4){cvtpk(p0[0], p0[1]), cvtpk(p0[2], p0[3]), cvtpk(p0[4], p0[5]), cvtpk(p0[6], p0[7])};
;             pw[1] = (u32x4){cvtpk(p0[8], p0[9]), cvtpk(p0[10], p0[11]), cvtpk(p0[12], p0[13]), cvtpk(p0[14], p0[15])};
;             pw[2] = (u32x4){cvtpk(p1[0], p1[1]), cvtpk(p1[2], p1[3]), cvtpk(p1[4], p1[5]), cvtpk(p1[6], p1[7])};
;             pw[3] = (u32x4){cvtpk(p1[8], p1[9]), cvtpk(p1[10], p1[11]), cvtpk(p1[12], p1[13]), cvtpk(p1[14], p1[15])};
;             FA_SB();
; #pragma unroll
;             for (int s = 0; s < 4; ++s) {
;                 if (s < 3) {
; #pragma unroll
;                     for (int db = 0; db < NDB; ++db) vf[(s + 1) & 1][db] = *(const FLAS u32x4*)(vb + db * 32 * VPITCH + (s + 1) * 32); }
; #pragma unroll
;                 for (int db = 0; db < NDB; ++db) o[db] = __builtin_amdgcn_mfma_f32_32x32x16_bf16(__builtin_bit_cast(bf16x8, vf[s & 1][db]), __builtin_bit_cast(bf16x8, pw[s]), o[db], 0, 0, 0);
;                 FA_SB();
;             }
.LBB0_508:
	v_exp_f32_e32 v132, v132
	v_exp_f32_e32 v133, v133
	v_exp_f32_e32 v130, v130
	v_exp_f32_e32 v131, v131
	v_add_f32_e32 v61, v132, v133
	v_cvt_pk_bf16_f32 v32, v132, v133
	v_exp_f32_e32 v128, v128
	v_add_f32_e32 v61, v130, v61
	v_exp_f32_e32 v129, v129
	v_add_f32_e32 v61, v131, v61
	v_cvt_pk_bf16_f32 v33, v130, v131
	v_exp_f32_e32 v126, v126
	v_add_f32_e32 v61, v128, v61
	v_exp_f32_e32 v127, v127
	v_add_f32_e32 v61, v129, v61
	v_cvt_pk_bf16_f32 v34, v128, v129
	v_exp_f32_e32 v124, v124
	v_add_f32_e32 v61, v126, v61
	v_exp_f32_e32 v125, v125
	v_add_f32_e32 v61, v127, v61
	v_cvt_pk_bf16_f32 v35, v126, v127
	v_exp_f32_e32 v122, v122
	v_add_f32_e32 v61, v124, v61
	v_exp_f32_e32 v123, v123
	v_add_f32_e32 v61, v125, v61
	v_cvt_pk_bf16_f32 v36, v124, v125
	v_exp_f32_e32 v118, v118
	v_add_f32_e32 v61, v122, v61
	v_exp_f32_e32 v119, v119
	v_add_f32_e32 v61, v123, v61
	v_cvt_pk_bf16_f32 v37, v122, v123
	v_exp_f32_e32 v112, v112
	v_add_f32_e32 v61, v118, v61
	v_exp_f32_e32 v113, v113
	v_add_f32_e32 v61, v119, v61
	v_cvt_pk_bf16_f32 v38, v118, v119
	v_exp_f32_e32 v120, v120
	v_add_f32_e32 v61, v112, v61
	v_exp_f32_e32 v121, v121
	v_add_f32_e32 v61, v113, v61
	v_cvt_pk_bf16_f32 v39, v112, v113
	v_exp_f32_e32 v116, v116
	v_add_f32_e32 v61, v120, v61
	v_exp_f32_e32 v117, v117
	v_add_f32_e32 v61, v121, v61
	v_cvt_pk_bf16_f32 v40, v120, v121
	v_exp_f32_e32 v114, v114
	v_add_f32_e32 v61, v116, v61
	v_exp_f32_e32 v115, v115
	v_add_f32_e32 v61, v117, v61
	v_cvt_pk_bf16_f32 v41, v116, v117
	v_exp_f32_e32 v110, v110
	v_add_f32_e32 v61, v114, v61
	v_exp_f32_e32 v111, v111
	v_add_f32_e32 v61, v115, v61
	v_cvt_pk_bf16_f32 v42, v114, v115
	v_exp_f32_e32 v108, v108
	v_add_f32_e32 v61, v110, v61
	v_exp_f32_e32 v109, v109
	v_add_f32_e32 v61, v111, v61
	v_cvt_pk_bf16_f32 v43, v110, v111
	v_exp_f32_e32 v106, v106
	v_add_f32_e32 v61, v108, v61
	v_exp_f32_e32 v107, v107
	v_add_f32_e32 v61, v109, v61
	v_cvt_pk_bf16_f32 v44, v108, v109
	v_exp_f32_e32 v104, v104
	v_add_f32_e32 v61, v106, v61
	v_exp_f32_e32 v105, v105
	v_add_f32_e32 v61, v107, v61
	v_cvt_pk_bf16_f32 v45, v106, v107
	v_exp_f32_e32 v102, v102
	v_add_f32_e32 v61, v104, v61
	v_exp_f32_e32 v103, v103
	v_add_f32_e32 v61, v105, v61
	v_cvt_pk_bf16_f32 v46, v104, v105
	v_add_f32_e32 v61, v102, v61
	v_add_f32_e32 v61, v103, v61
	v_cvt_pk_bf16_f32 v47, v102, v103
	s_waitcnt lgkmcnt(1)
	v_mfma_f32_32x32x16_bf16 v[0:15], v[92:95], v[32:35], v[0:15]
	ds_read_b128 v[48:51], v149 offset:16416
	ds_read_b128 v[52:55], v149 offset:21024
	s_waitcnt lgkmcnt(2)
	v_mfma_f32_32x32x16_bf16 v[16:31], v[88:91], v[32:35], v[16:31]
	s_waitcnt lgkmcnt(1)
	v_mfma_f32_32x32x16_bf16 v[0:15], v[48:51], v[36:39], v[0:15]
	ds_read_b128 v[32:35], v149 offset:16448
	ds_read_b128 v[48:51], v149 offset:21056
	s_waitcnt lgkmcnt(2)
	v_mfma_f32_32x32x16_bf16 v[16:31], v[52:55], v[36:39], v[16:31]
	s_waitcnt lgkmcnt(1)
	v_mfma_f32_32x32x16_bf16 v[0:15], v[32:35], v[40:43], v[0:15]
	ds_read_b128 v[32:35], v149 offset:16480
	ds_read_b128 v[36:39], v149 offset:21088
	s_waitcnt lgkmcnt(2)
	v_mfma_f32_32x32x16_bf16 v[16:31], v[48:51], v[40:43], v[16:31]
	s_waitcnt lgkmcnt(1)
	v_mfma_f32_32x32x16_bf16 v[0:15], v[32:35], v[44:47], v[0:15]
	s_waitcnt lgkmcnt(0)
	v_mfma_f32_32x32x16_bf16 v[16:31], v[36:39], v[44:47], v[16:31]
	v_add_f32_e32 v137, v137, v61
	s_mov_b64 s[6:7], 0
	s_andn2_b64 vcc, exec, s[4:5]
	s_cbranch_vccnz .LBB0_510

; template <int MODE> __device__ __forceinline__ void attn_unit(FLAS unsigned char* lds, const Unit u) {
;     ...
;     for (int t = u.t_lo; t < u.t_hi; ++t) {
;         const int cur = (t - u.t_lo) & 1;
;         const bool more = (t + 1 < u.t_hi);
;         if (more) { kreg = *(const u32x4*)(ksrc + (size_t)(t + 1) * 64 * u.ldk);
; #pragma unroll
;             for (int i = 0; i < NVR; ++i) vreg[i] = *(const u32x4*)(vsrc + (size_t)i * 64 * MTOK + (t + 1) * 64); }
;         const int k0 = t * 64;
;         bool active = true;
;         if (MODE == 1) active = (t >= rstart) && (t < rstart + 8);
;         if (MODE == 2) active = (k0 + 63 >= q0w - 1024) && (k0 <= q0w + 31 + 1024);
;         if (active) {
;             f32x16 p0, p1;
;             bf16x8 kf[8];
;             { const FLAS unsigned char* kb = lds + L_K + cur * KBUF;
; #pragma unroll
;               for (int d0 = 0; d0 < 4; ++d0) { const int ko = (2 * d0 + hi) * 1024 + ((r32 ^ (2 * d0 + hi)) * 16); kf[2 * d0] = *(const FLAS bf16x8*)(kb + ko); kf[2 * d0 + 1] = *(const FLAS bf16x8*)(kb + ko + 512); } }
;             float cb = 0.f; bool zinit = false;
;             if (MODE == 0) { const int dmin = k0 - (q0w + 31), dmax = k0 + 63 - q0w;
;                 if (dmin >= 559) { cb = L[LUT_C + 600]; zinit = true; } else if (dmax <= -559) { cb = L[LUT_C - 600]; zinit = true; } }
;             if (zinit) {
;                 const f32x16 z16 = {0.f,0.f,0.f,0.f,0.f,0.f,0.f,0.f,0.f,0.f,0.f,0.f,0.f,0.f,0.f,0.f};
;                 FA_SB();
;                 p0 = __builtin_amdgcn_mfma_f32_32x32x16_bf16(kf[0], qr[0], z16, 0, 0, 0); p1 = __builtin_amdgcn_mfma_f32_32x32x16_bf16(kf[1], qr[0], z16, 0, 0, 0);
; #pragma unroll
;                 for (int d0 = 1; d0 < 4; ++d0) { p0 = __builtin_amdgcn_mfma_f32_32x32x16_bf16(kf[2 * d0], qr[d0], p0, 0, 0, 0); p1 = __builtin_amdgcn_mfma_f32_32x32x16_bf16(kf[2 * d0 + 1], qr[d0], p1, 0, 0, 0); }
;             } else {
;                 if (MODE == 0 || MODE == 2) { const FLAS float* lp = L + (k0 - q + LUT_C + 4 * hi);
; #pragma unroll
;                     for (int r = 0; r < 16; ++r) { p0[r] = lp[(r & 3) + 8 * (r >> 2)]; p1[r] = lp[32 + (r & 3) + 8 * (r >> 2)]; }
;                 } else { const FLAS float* lp = L + ((t - gi + 7) * 128 + 63 - qc + 4 * hi);
; #pragma unroll
;                     for (int r = 0; r < 16; ++r) { const int kc = (r & 3) + 8 * (r >> 2) + 4 * hi;
.LBB0_530:
	s_and_b32 s21, s14, 1
	s_cmp_ge_i32 s14, s26
	s_cselect_b64 vcc, -1, 0
	s_cmp_lt_i32 s14, s12
	s_cselect_b64 s[28:29], -1, 0
	s_and_b64 s[28:29], vcc, s[28:29]
	s_andn2_b64 vcc, exec, s[28:29]
	s_cbranch_vccnz .LBB0_539
	s_lshl_b32 s15, s21, 13
	s_add_i32 s15, s15, 0
	v_add3_u32 v32, s15, v138, v139
	ds_read_b128 v[88:91], v32
	ds_read_b128 v[92:95], v32 offset:512
	v_add3_u32 v32, s15, v140, v141
	ds_read_b128 v[102:105], v32
	ds_read_b128 v[106:109], v32 offset:512
	v_add3_u32 v32, s15, v142, v143
	ds_read_b128 v[110:113], v32
	ds_read_b128 v[114:117], v32 offset:512
	v_add3_u32 v32, s15, v144, v145
	ds_read_b128 v[118:121], v32
	ds_read_b128 v[122:125], v32 offset:512
	ds_read2_b32 v[32:33], v147 offset1:1
	ds_read2_b32 v[34:35], v147 offset0:2 offset1:3
	ds_read2_b32 v[36:37], v147 offset0:8 offset1:9
	ds_read2_b32 v[38:39], v147 offset0:10 offset1:11
	ds_read2_b32 v[48:49], v147 offset0:32 offset1:33
	ds_read2_b32 v[50:51], v147 offset0:34 offset1:35
	ds_read2_b32 v[52:53], v147 offset0:40 offset1:41
	ds_read2_b32 v[54:55], v147 offset0:42 offset1:43
	ds_read2_b32 v[40:41], v147 offset0:16 offset1:17
	ds_read2_b32 v[42:43], v147 offset0:18 offset1:19
	ds_read2_b32 v[44:45], v147 offset0:24 offset1:25
	ds_read2_b32 v[46:47], v147 offset0:26 offset1:27
	ds_read2_b32 v[56:57], v147 offset0:48 offset1:49
	ds_read2_b32 v[58:59], v147 offset0:50 offset1:51
	ds_read2_b32 v[60:61], v147 offset0:56 offset1:57
	ds_read2_b32 v[62:63], v147 offset0:58 offset1:59
	s_xor_b64 s[22:23], s[22:23], -1
	s_waitcnt lgkmcnt(14)
	v_cndmask_b32_e64 v34, v242, v34, s[66:67]
	v_cndmask_b32_e64 v33, v242, v33, s[68:69]
	v_cndmask_b32_e64 v32, v242, v32, s[70:71]
	v_cndmask_b32_e64 v35, v242, v35, s[64:65]
	s_waitcnt lgkmcnt(13)
	v_cndmask_b32_e64 v36, v242, v36, s[62:63]
	v_cndmask_b32_e64 v37, v242, v37, s[60:61]
	s_waitcnt lgkmcnt(12)
	v_cndmask_b32_e64 v38, v242, v38, s[58:59]
	v_cndmask_b32_e64 v39, v242, v39, s[56:57]
	s_waitcnt lgkmcnt(7)
	v_cndmask_b32_e64 v40, v242, v40, s[54:55]
	v_cndmask_b32_e64 v41, v242, v41, s[52:53]
	s_waitcnt lgkmcnt(6)
	v_cndmask_b32_e64 v42, v242, v42, s[50:51]
	v_cndmask_b32_e64 v43, v242, v43, s[48:49]
	s_waitcnt lgkmcnt(5)
	v_cndmask_b32_e64 v44, v242, v44, s[46:47]
	v_cndmask_b32_e64 v45, v242, v45, s[44:45]
	s_waitcnt lgkmcnt(4)
	v_cndmask_b32_e64 v46, v242, v46, s[42:43]
	v_cndmask_b32_e64 v47, v242, v47, s[40:41]
	v_cndmask_b32_e64 v50, v242, v50, s[4:5]
	v_cndmask_b32_e64 v49, v242, v49, s[6:7]
	v_cndmask_b32_e64 v48, v242, v48, s[8:9]
	v_cndmask_b32_e64 v51, v242, v51, s[96:97]
	v_cndmask_b32_e64 v52, v242, v52, s[94:95]
	v_cndmask_b32_e64 v53, v242, v53, s[92:93]
	v_cndmask_b32_e64 v54, v242, v54, s[90:91]
	v_cndmask_b32_e64 v55, v242, v55, s[88:89]
	s_waitcnt lgkmcnt(3)
	v_cndmask_b32_e64 v56, v242, v56, s[86:87]
	v_cndmask_b32_e64 v57, v242, v57, s[84:85]
	s_waitcnt lgkmcnt(2)
	v_cndmask_b32_e64 v58, v242, v58, s[82:83]
	v_cndmask_b32_e64 v59, v242, v59, s[80:81]
	s_waitcnt lgkmcnt(1)
	v_cndmask_b32_e64 v60, v242, v60, s[78:79]
	v_cndmask_b32_e64 v61, v242, v61, s[76:77]
	s_waitcnt lgkmcnt(0)
	v_cndmask_b32_e64 v62, v242, v62, s[74:75]
	v_cndmask_b32_e64 v63, v242, v63, s[72:73]
	v_mfma_f32_32x32x16_bf16 v[32:47], v[88:91], v[64:67], v[32:47]
	s_mul_i32 s15, s21, 0x4800
	v_add_u32_e32 v149, s15, v137
	v_mfma_f32_32x32x16_bf16 v[48:63], v[92:95], v[64:67], v[48:63]
	ds_read_b128 v[92:95], v149 offset:16384
	ds_read_b128 v[88:91], v149 offset:20992
	v_mfma_f32_32x32x16_bf16 v[32:47], v[102:105], v[68:71], v[32:47]
	v_mfma_f32_32x32x16_bf16 v[48:63], v[106:109], v[68:71], v[48:63]
	v_mfma_f32_32x32x16_bf16 v[32:47], v[110:113], v[72:75], v[32:47]
	v_mfma_f32_32x32x16_bf16 v[48:63], v[114:117], v[72:75], v[48:63]
	v_mfma_f32_32x32x16_bf16 v[32:47], v[118:121], v[76:79], v[32:47]
	v_mfma_f32_32x32x16_bf16 v[48:63], v[122:125], v[76:79], v[48:63]
	s_and_b32 s14, s14, 3
	s_cmp_lg_u32 s14, 0
	s_cselect_b64 s[14:15], -1, 0
	v_sub_f32_e32 v102, 0, v148
	s_and_b64 s[14:15], s[22:23], s[14:15]
	s_nop 5
	v_add_f32_e32 v132, v102, v32
	v_add_f32_e32 v133, v102, v33
	v_add_f32_e32 v120, v102, v48
	v_add_f32_e32 v121, v102, v49
	v_add_f32_e32 v130, v102, v34
	v_add_f32_e32 v131, v102, v35
	v_add_f32_e32 v116, v102, v50
	v_add_f32_e32 v117, v102, v51
	v_add_f32_e32 v128, v102, v36
	v_add_f32_e32 v129, v102, v37
	v_add_f32_e32 v114, v102, v52
	v_add_f32_e32 v115, v102, v53
	v_add_f32_e32 v126, v102, v38
	v_add_f32_e32 v127, v102, v39
	v_add_f32_e32 v110, v102, v54
	v_add_f32_e32 v111, v102, v55
	v_add_f32_e32 v124, v102, v40
	v_add_f32_e32 v125, v102, v41
	v_add_f32_e32 v108, v102, v56
	v_add_f32_e32 v109, v102, v57
	v_add_f32_e32 v122, v102, v42
	v_add_f32_e32 v123, v102, v43
	v_add_f32_e32 v106, v102, v58
	v_add_f32_e32 v107, v102, v59
	v_add_f32_e32 v118, v102, v44
	v_add_f32_e32 v119, v102, v45
	v_add_f32_e32 v104, v102, v60
	v_add_f32_e32 v105, v102, v61
	v_add_f32_e32 v112, v102, v46
	v_add_f32_e32 v113, v102, v47
	v_add_f32_e32 v103, v102, v63
	v_add_f32_e32 v102, v102, v62
	s_and_b64 vcc, exec, s[14:15]
	s_cbranch_vccnz .LBB0_538
; __device__ __forceinline__ float xhalf_max(float m) { unsigned a = __builtin_bit_cast(unsigned, m), b = a; xswap(a, b); return __builtin_fmaxf(__builtin_bit_cast(float, a), __builtin_bit_cast(float, b)); }
; template <int MODE> __device__ __forceinline__ void attn_unit(FLAS unsigned char* lds, const Unit u) {
;     ...
;             if (first || (((t - u.t_lo) & 3) == 0)) {
;             float rm = __builtin_fmaxf(p0[0], p1[0]);
; #pragma unroll
;             for (int r = 1; r < 16; ++r) rm = __builtin_fmaxf(rm, __builtin_fmaxf(p0[r], p1[r]));
;             rm = xhalf_max(rm);
;             if (first) {
;                 const float dl = __builtin_fmaxf(rm, -1000.0f); mrun = dl;
; #pragma unroll
;                 for (int r = 0; r < 16; ++r) { p0[r] = p0[r] - dl; p1[r] = p1[r] - dl; }
;                 first = false;
;             } else if (__any(rm > 8.0f)) { const float dl = __builtin_fmaxf(rm, 0.0f); const float f = __builtin_amdgcn_exp2f(-dl); mrun += dl; lsum *= f;
; #pragma unroll
;                 for (int i = 0; i < NDB; ++i) o[i] = o[i] * f;
; #pragma unroll
;                 for (int r = 0; r < 16; ++r) { p0[r] = p0[r] - dl; p1[r] = p1[r] - dl; } }
	v_max_f32_e32 v32, v121, v121
	v_max_f32_e32 v33, v133, v133
	v_max_f32_e32 v32, v33, v32
	v_max_f32_e32 v33, v116, v116
	v_max_f32_e32 v34, v130, v130
	v_max_f32_e32 v33, v34, v33
	v_max_f32_e32 v34, v117, v117
	v_max_f32_e32 v35, v131, v131
	v_max3_f32 v32, v132, v120, v32
	v_max_f32_e32 v34, v35, v34
	v_max3_f32 v32, v32, v33, v34
	v_max_f32_e32 v33, v114, v114
	v_max_f32_e32 v34, v128, v128
	v_max_f32_e32 v33, v34, v33
	v_max_f32_e32 v34, v115, v115
	v_max_f32_e32 v35, v129, v129
	v_max_f32_e32 v34, v35, v34
	v_max3_f32 v32, v32, v33, v34
	v_max_f32_e32 v33, v110, v110
	v_max_f32_e32 v34, v126, v126
	v_max_f32_e32 v33, v34, v33
	v_max_f32_e32 v34, v111, v111
	v_max_f32_e32 v35, v127, v127
	v_max_f32_e32 v34, v35, v34
	v_max3_f32 v32, v32, v33, v34
	v_max_f32_e32 v33, v108, v108
	v_max_f32_e32 v34, v124, v124
	v_max_f32_e32 v33, v34, v33
	v_max_f32_e32 v34, v109, v109
	v_max_f32_e32 v35, v125, v125
	v_max_f32_e32 v34, v35, v34
	v_max3_f32 v32, v32, v33, v34
	v_max_f32_e32 v33, v106, v106
	v_max_f32_e32 v34, v122, v122
	v_max_f32_e32 v33, v34, v33
	v_max_f32_e32 v34, v107, v107
	v_max_f32_e32 v35, v123, v123
	v_max_f32_e32 v34, v35, v34
	v_max3_f32 v32, v32, v33, v34
	v_max_f32_e32 v33, v104, v104
	v_max_f32_e32 v34, v118, v118
	v_max_f32_e32 v33, v34, v33
	v_max_f32_e32 v34, v105, v105
	v_max_f32_e32 v35, v119, v119
	v_max_f32_e32 v34, v35, v34
	v_max3_f32 v32, v32, v33, v34
	v_max_f32_e32 v33, v102, v102
	v_max_f32_e32 v34, v112, v112
	v_max_f32_e32 v33, v34, v33
	v_max_f32_e32 v34, v103, v103
	v_max_f32_e32 v35, v113, v113
	v_max_f32_e32 v34, v35, v34
	v_max3_f32 v32, v32, v33, v34
	v_mov_b32_e32 v33, v32
	s_nop 1
	v_permlane32_swap_b32 v33, v32
	s_nop 1
	s_mov_b64 s[14:15], -1
	v_max_f32_e32 v32, v32, v32
	v_max_f32_e32 v33, v33, v33
	v_max_f32_e32 v163, v33, v32
	s_and_b64 vcc, exec, s[22:23]
	s_cbranch_vccz .LBB0_535
	s_mov_b32 s14, 0x41000000
	v_cmp_lt_f32_e32 vcc, s14, v163
	s_cbranch_vccz .LBB0_538
	v_max_f32_e32 v32, v163, v163
	v_max_f32_e32 v167, 0, v32
	v_exp_f32_e64 v184, -v167
	v_add_f32_e32 v148, v148, v167
	v_sub_f32_e32 v166, v132, v167
	v_sub_f32_e32 v165, v133, v167
	v_pk_mul_f32 v[62:63], v[30:31], v[184:185] op_sel_hi:[1,0]
	v_pk_mul_f32 v[60:61], v[28:29], v[184:185] op_sel_hi:[1,0]
	v_pk_mul_f32 v[58:59], v[26:27], v[184:185] op_sel_hi:[1,0]
	v_pk_mul_f32 v[56:57], v[24:25], v[184:185] op_sel_hi:[1,0]
	v_pk_mul_f32 v[54:55], v[22:23], v[184:185] op_sel_hi:[1,0]
	v_pk_mul_f32 v[52:53], v[20:21], v[184:185] op_sel_hi:[1,0]
	v_pk_mul_f32 v[50:51], v[18:19], v[184:185] op_sel_hi:[1,0]
	v_pk_mul_f32 v[48:49], v[16:17], v[184:185] op_sel_hi:[1,0]
	v_pk_mul_f32 v[46:47], v[14:15], v[184:185] op_sel_hi:[1,0]
	v_pk_mul_f32 v[44:45], v[12:13], v[184:185] op_sel_hi:[1,0]
	v_pk_mul_f32 v[42:43], v[10:11], v[184:185] op_sel_hi:[1,0]
	v_pk_mul_f32 v[40:41], v[8:9], v[184:185] op_sel_hi:[1,0]
	v_pk_mul_f32 v[38:39], v[6:7], v[184:185] op_sel_hi:[1,0]
	v_pk_mul_f32 v[36:37], v[4:5], v[184:185] op_sel_hi:[1,0]
	v_pk_mul_f32 v[34:35], v[2:3], v[184:185] op_sel_hi:[1,0]
	v_pk_mul_f32 v[32:33], v[0:1], v[184:185] op_sel_hi:[1,0]
	v_sub_f32_e32 v164, v130, v167
	v_sub_f32_e32 v162, v131, v167
	v_sub_f32_e32 v161, v128, v167
	v_sub_f32_e32 v160, v129, v167
	v_sub_f32_e32 v159, v126, v167
	v_sub_f32_e32 v158, v127, v167
	v_sub_f32_e32 v157, v124, v167
	v_sub_f32_e32 v156, v125, v167
	v_sub_f32_e32 v155, v122, v167
	v_sub_f32_e32 v154, v123, v167
	v_sub_f32_e32 v153, v118, v167
	v_sub_f32_e32 v152, v119, v167
	v_sub_f32_e32 v151, v112, v167
	v_sub_f32_e32 v150, v113, v167
	v_sub_f32_e32 v182, v120, v167
	v_sub_f32_e32 v181, v121, v167
	v_sub_f32_e32 v180, v116, v167
	v_sub_f32_e32 v179, v117, v167
	v_sub_f32_e32 v178, v114, v167
	v_sub_f32_e32 v177, v115, v167
	v_sub_f32_e32 v176, v110, v167
	v_sub_f32_e32 v175, v111, v167
	v_sub_f32_e32 v174, v108, v167
	v_sub_f32_e32 v173, v109, v167
	v_sub_f32_e32 v172, v106, v167
	v_sub_f32_e32 v171, v107, v167
	v_sub_f32_e32 v170, v104, v167
	v_sub_f32_e32 v169, v105, v167
	v_sub_f32_e32 v168, v102, v167
	v_sub_f32_e32 v167, v103, v167
	v_mul_f32_e32 v183, v146, v184
	s_mov_b64 s[14:15], 0

; #define FLAS __attribute__((address_space(3)))
; #define FA_SB() __builtin_amdgcn_sched_barrier(0)
; __device__ __forceinline__ unsigned cvtpk(float lo, float hi) { f32x2_t v = {lo, hi}; bf16x2_t b = __builtin_convertvector(v, bf16x2_t); return __builtin_bit_cast(unsigned, b); }
; template <int MODE> __device__ __forceinline__ void attn_unit(FLAS unsigned char* lds, const Unit u) {
;     ...
;             float ps = 0.f;
; #pragma unroll
;             for (int r = 0; r < 16; ++r) { p0[r] = __builtin_amdgcn_exp2f(p0[r]); p1[r] = __builtin_amdgcn_exp2f(p1[r]); ps += p0[r] + p1[r]; }
;             lsum += ps;
;             u32x4 pw[4];
;             pw[0] = (u32x4){cvtpk(p0[0], p0[1]), cvtpk(p0[2], p0[3]), cvtpk(p0[4], p0[5]), cvtpk(p0[6], p0[7])};
;             pw[1] = (u32x4){cvtpk(p0[8], p0[9]), cvtpk(p0[10], p0[11]), cvtpk(p0[12], p0[13]), cvtpk(p0[14], p0[15])};
;             pw[2] = (u32x4){cvtpk(p1[0], p1[1]), cvtpk(p1[2], p1[3]), cvtpk(p1[4], p1[5]), cvtpk(p1[6], p1[7])};
;             pw[3] = (u32x4){cvtpk(p1[8], p1[9]), cvtpk(p1[10], p1[11]), cvtpk(p1[12], p1[13]), cvtpk(p1[14], p1[15])};
;             FA_SB();
; #pragma unroll
;             for (int s = 0; s < 4; ++s) {
;                 if (s < 3) {
; #pragma unroll
;                     for (int db = 0; db < NDB; ++db) vf[(s + 1) & 1][db] = *(const FLAS u32x4*)(vb + db * 32 * VPITCH + (s + 1) * 32); }
; #pragma unroll
;                 for (int db = 0; db < NDB; ++db) o[db] = __builtin_amdgcn_mfma_f32_32x32x16_bf16(__builtin_bit_cast(bf16x8, vf[s & 1][db]), __builtin_bit_cast(bf16x8, pw[s]), o[db], 0, 0, 0);
;                 FA_SB();
;             }
.LBB0_538:
	v_exp_f32_e32 v132, v132
	v_exp_f32_e32 v133, v133
	v_exp_f32_e32 v130, v130
	v_exp_f32_e32 v131, v131
	v_add_f32_e32 v61, v132, v133
	v_cvt_pk_bf16_f32 v32, v132, v133
	v_exp_f32_e32 v128, v128
	v_add_f32_e32 v61, v130, v61
	v_exp_f32_e32 v129, v129
	v_add_f32_e32 v61, v131, v61
	v_cvt_pk_bf16_f32 v33, v130, v131
	v_exp_f32_e32 v126, v126
	v_add_f32_e32 v61, v128, v61
	v_exp_f32_e32 v127, v127
	v_add_f32_e32 v61, v129, v61
	v_cvt_pk_bf16_f32 v34, v128, v129
	v_exp_f32_e32 v124, v124
	v_add_f32_e32 v61, v126, v61
	v_exp_f32_e32 v125, v125
	v_add_f32_e32 v61, v127, v61
	v_cvt_pk_bf16_f32 v35, v126, v127
	v_exp_f32_e32 v122, v122
	v_add_f32_e32 v61, v124, v61
	v_exp_f32_e32 v123, v123
	v_add_f32_e32 v61, v125, v61
	v_cvt_pk_bf16_f32 v36, v124, v125
	v_exp_f32_e32 v118, v118
	v_add_f32_e32 v61, v122, v61
	v_exp_f32_e32 v119, v119
	v_add_f32_e32 v61, v123, v61
	v_cvt_pk_bf16_f32 v37, v122, v123
	v_exp_f32_e32 v112, v112
	v_add_f32_e32 v61, v118, v61
	v_exp_f32_e32 v113, v113
	v_add_f32_e32 v61, v119, v61
	v_cvt_pk_bf16_f32 v38, v118, v119
	v_exp_f32_e32 v120, v120
	v_add_f32_e32 v61, v112, v61
	v_exp_f32_e32 v121, v121
	v_add_f32_e32 v61, v113, v61
	v_cvt_pk_bf16_f32 v39, v112, v113
	v_exp_f32_e32 v116, v116
	v_add_f32_e32 v61, v120, v61
	v_exp_f32_e32 v117, v117
	v_add_f32_e32 v61, v121, v61
	v_cvt_pk_bf16_f32 v40, v120, v121
	v_exp_f32_e32 v114, v114
	v_add_f32_e32 v61, v116, v61
	v_exp_f32_e32 v115, v115
	v_add_f32_e32 v61, v117, v61
	v_cvt_pk_bf16_f32 v41, v116, v117
	v_exp_f32_e32 v110, v110
	v_add_f32_e32 v61, v114, v61
	v_exp_f32_e32 v111, v111
	v_add_f32_e32 v61, v115, v61
	v_cvt_pk_bf16_f32 v42, v114, v115
	v_exp_f32_e32 v108, v108
	v_add_f32_e32 v61, v110, v61
	v_exp_f32_e32 v109, v109
	v_add_f32_e32 v61, v111, v61
	v_cvt_pk_bf16_f32 v43, v110, v111
	v_exp_f32_e32 v106, v106
	v_add_f32_e32 v61, v108, v61
	v_exp_f32_e32 v107, v107
	v_add_f32_e32 v61, v109, v61
	v_cvt_pk_bf16_f32 v44, v108, v109
	v_exp_f32_e32 v104, v104
	v_add_f32_e32 v61, v106, v61
	v_exp_f32_e32 v105, v105
	v_add_f32_e32 v61, v107, v61
	v_cvt_pk_bf16_f32 v45, v106, v107
	v_exp_f32_e32 v102, v102
	v_add_f32_e32 v61, v104, v61
	v_exp_f32_e32 v103, v103
	v_add_f32_e32 v61, v105, v61
	v_cvt_pk_bf16_f32 v46, v104, v105
	v_add_f32_e32 v61, v102, v61
	v_add_f32_e32 v61, v103, v61
	v_cvt_pk_bf16_f32 v47, v102, v103
	s_waitcnt lgkmcnt(1)
	v_mfma_f32_32x32x16_bf16 v[0:15], v[92:95], v[32:35], v[0:15]
	ds_read_b128 v[48:51], v149 offset:16416
	ds_read_b128 v[52:55], v149 offset:21024
	s_waitcnt lgkmcnt(2)
	v_mfma_f32_32x32x16_bf16 v[16:31], v[88:91], v[32:35], v[16:31]
	s_waitcnt lgkmcnt(1)
	v_mfma_f32_32x32x16_bf16 v[0:15], v[48:51], v[36:39], v[0:15]
	ds_read_b128 v[32:35], v149 offset:16448
	ds_read_b128 v[48:51], v149 offset:21056
	s_waitcnt lgkmcnt(2)
	v_mfma_f32_32x32x16_bf16 v[16:31], v[52:55], v[36:39], v[16:31]
	s_waitcnt lgkmcnt(1)
	v_mfma_f32_32x32x16_bf16 v[0:15], v[32:35], v[40:43], v[0:15]
	ds_read_b128 v[32:35], v149 offset:16480
	ds_read_b128 v[36:39], v149 offset:21088
	s_waitcnt lgkmcnt(2)
	v_mfma_f32_32x32x16_bf16 v[16:31], v[48:51], v[40:43], v[16:31]
	s_waitcnt lgkmcnt(1)
	v_mfma_f32_32x32x16_bf16 v[0:15], v[32:35], v[44:47], v[0:15]
	s_waitcnt lgkmcnt(0)
	v_mfma_f32_32x32x16_bf16 v[16:31], v[36:39], v[44:47], v[16:31]
	v_add_f32_e32 v146, v146, v61
	s_mov_b64 s[22:23], 0
